# v073 stack + main attention per-tile K/V LDS-DMA in SGPR-base form (six 64-bit VALU address ops per tile removed)
# speedup vs baseline: 1.0074x; 1.0017x over previous
.LBB0_709:
	s_cmp_lt_u32 s40, 31
	s_cselect_b32 s2, 0, 0xffffffe0
	s_cselect_b32 s8, s12, s13
	s_add_i32 s2, s2, s40
	s_lshl_b32 s2, s2, 6
	s_add_i32 s2, s2, s8
	s_add_i32 s2, s2, 64
	s_mul_hi_u32 s9, s2, 0x1600
	s_mulk_i32 s2, 0x1600
	s_add_u32 s8, s36, s2
	s_addc_u32 s9, s38, s9
	s_lshl_b32 s2, s3, 14
	s_xor_b32 s3, s2, 0x4000
	s_add_u32 s10, s8, 0x1200
	s_addc_u32 s11, s9, 0
	s_add_u32 s8, s8, s26
	s_addc_u32 s9, s9, s27
	s_add_i32 s3, s39, s3
	s_add_i32 m0, s3, 0x8000
	s_nop 0
	global_load_lds_dwordx4 v0, s[8:9]
	s_mov_b32 m0, s3
	s_nop 0
	global_load_lds_dwordx4 v196, s[10:11]
	s_add_i32 m0, s3, 0x8400
	s_nop 0
	global_load_lds_dwordx4 v198, s[8:9]
	s_add_i32 m0, s3, 0x400
	s_nop 0
	global_load_lds_dwordx4 v200, s[10:11]
	s_andn2_b64 vcc, exec, s[6:7]
	s_add_i32 s3, s2, 0
	s_cbranch_vccz .LBB0_702
